# v10 with G1 epilogue staged through LDS (swizzled tile image, row-contiguous 16-byte stores, full cache lines)
# speedup vs baseline: 1.0175x; 1.0175x over previous
; __device__ __forceinline__ bf16_t f2bf(float f) { return (bf16_t)(pack2(f, 0.f) & 0xffffu); }
; __device__ __forceinline__ float siluf_(float x) { return x * __builtin_amdgcn_rcpf(1.f + __expf(-x)); }
; template <int EPI>
; __device__ __forceinline__ void gemm_tile8p(const bf16_t* __restrict__ Ag, const bf16_t* __restrict__ Bg, int K, int nt, int brow, int bcol,
;                                             char* smem, void* outp, int ldo, int nvalid, int rowoff, int rowlim) {
;     ...
; #pragma unroll
;   for (int ai = 0; ai < 2; ++ai)
; #pragma unroll
;     for (int m = 0; m < 4; ++m)
; #pragma unroll
;       for (int j = 0; j < 4; ++j) {
;         const int rl = ai * HALF + wr * 64 + m * 16 + fq * 4 + j;
;         const size_t orow = (size_t)(rowoff + rl) * ldo;
;         if (EPI == EPI_GLU) {
; #pragma unroll
;           for (int n = 0; n < 2; ++n) {
;             const int col = (bcol >> 8) * 128 + wc * 32 + n * 16 + fr;
;             const float g = acc[ai][0][m][n][j], u = acc[ai][1][m][n][j];
;             if (rl < rowlim) ((bf16_t*)outp)[orow + col] = f2bf(siluf_(g) * u);
;           }
;         } else {
; #pragma unroll
;           for (int bj = 0; bj < 2; ++bj)
; #pragma unroll
;             for (int n = 0; n < 2; ++n) {
;               const int col = bcol + bj * HALF + wc * 32 + n * 16 + fr;
;               const float v = acc[ai][bj][m][n][j];
;               if (EPI == EPI_BF16) { if (rl < rowlim && col < nvalid) ((bf16_t*)outp)[orow + col] = f2bf(v); }
;               else { if (rl < rowlim) ((float*)outp)[orow + col] = v; }
;             }
;         }
;         __builtin_amdgcn_sched_barrier(0);
;       }
.LBB0_1069:
	s_or_b64 exec, exec, s[2:3]
	s_sub_i32 s4, 0x4080, s48
	v_or_b32_e32 v160, v136, v134
	v_lshlrev_b32_e32 v160, 9, v160
	v_and_b32_e32 v161, 1, v135
	v_lshl_or_b32 v160, v161, 3, v160
	v_lshrrev_b32_e32 v161, 1, v135
	v_lshl_or_b32 v162, v133, 2, v161
	v_xor_b32_e32 v162, v162, v134
	v_lshl_add_u32 v164, v162, 4, v160
	v_xor_b32_e32 v163, 2, v162
	v_lshl_add_u32 v165, v163, 4, v160
	v_add_u32_e32 v166, 0x100, v164
	v_add_u32_e32 v167, 0x100, v165
	v_add_u32_e32 v168, 0x10000, v164
	v_add_u32_e32 v169, 0x10000, v165
	v_add_u32_e32 v170, 0x10000, v166
	v_add_u32_e32 v171, 0x10000, v167
	v_cvt_pk_bf16_f32 v176, v124, v125
	v_cvt_pk_bf16_f32 v177, v126, v127
	v_cvt_pk_bf16_f32 v178, v116, v117
	v_cvt_pk_bf16_f32 v179, v118, v119
	v_cvt_pk_bf16_f32 v180, v120, v121
	v_cvt_pk_bf16_f32 v181, v122, v123
	v_cvt_pk_bf16_f32 v182, v112, v113
	v_cvt_pk_bf16_f32 v183, v114, v115
	ds_write_b64 v164, v[176:177]
	ds_write_b64 v165, v[178:179]
	ds_write_b64 v166, v[180:181]
	ds_write_b64 v167, v[182:183]
	v_cvt_pk_bf16_f32 v184, v108, v109
	v_cvt_pk_bf16_f32 v185, v110, v111
	v_cvt_pk_bf16_f32 v186, v100, v101
	v_cvt_pk_bf16_f32 v187, v102, v103
	v_cvt_pk_bf16_f32 v188, v104, v105
	v_cvt_pk_bf16_f32 v189, v106, v107
	v_cvt_pk_bf16_f32 v190, v96, v97
	v_cvt_pk_bf16_f32 v191, v98, v99
	ds_write_b64 v166, v[184:185] offset:8192
	ds_write_b64 v167, v[186:187] offset:8192
	ds_write_b64 v164, v[188:189] offset:8192
	ds_write_b64 v165, v[190:191] offset:8192
	v_cvt_pk_bf16_f32 v176, v92, v93
	v_cvt_pk_bf16_f32 v177, v94, v95
	v_cvt_pk_bf16_f32 v178, v84, v85
	v_cvt_pk_bf16_f32 v179, v86, v87
	v_cvt_pk_bf16_f32 v180, v88, v89
	v_cvt_pk_bf16_f32 v181, v90, v91
	v_cvt_pk_bf16_f32 v182, v80, v81
	v_cvt_pk_bf16_f32 v183, v82, v83
	ds_write_b64 v164, v[176:177] offset:16384
	ds_write_b64 v165, v[178:179] offset:16384
	ds_write_b64 v166, v[180:181] offset:16384
	ds_write_b64 v167, v[182:183] offset:16384
	v_cvt_pk_bf16_f32 v184, v76, v77
	v_cvt_pk_bf16_f32 v185, v78, v79
	v_cvt_pk_bf16_f32 v186, v68, v69
	v_cvt_pk_bf16_f32 v187, v70, v71
	v_cvt_pk_bf16_f32 v188, v72, v73
	v_cvt_pk_bf16_f32 v189, v74, v75
	v_cvt_pk_bf16_f32 v190, v64, v65
	v_cvt_pk_bf16_f32 v191, v66, v67
	ds_write_b64 v166, v[184:185] offset:24576
	ds_write_b64 v167, v[186:187] offset:24576
	ds_write_b64 v164, v[188:189] offset:24576
	ds_write_b64 v165, v[190:191] offset:24576
	v_cvt_pk_bf16_f32 v176, v60, v61
	v_cvt_pk_bf16_f32 v177, v62, v63
	v_cvt_pk_bf16_f32 v178, v52, v53
	v_cvt_pk_bf16_f32 v179, v54, v55
	v_cvt_pk_bf16_f32 v180, v56, v57
	v_cvt_pk_bf16_f32 v181, v58, v59
	v_cvt_pk_bf16_f32 v182, v48, v49
	v_cvt_pk_bf16_f32 v183, v50, v51
	ds_write_b64 v168, v[176:177]
	ds_write_b64 v169, v[178:179]
	ds_write_b64 v170, v[180:181]
	ds_write_b64 v171, v[182:183]
	v_cvt_pk_bf16_f32 v184, v44, v45
	v_cvt_pk_bf16_f32 v185, v46, v47
	v_cvt_pk_bf16_f32 v186, v36, v37
	v_cvt_pk_bf16_f32 v187, v38, v39
	v_cvt_pk_bf16_f32 v188, v40, v41
	v_cvt_pk_bf16_f32 v189, v42, v43
	v_cvt_pk_bf16_f32 v190, v32, v33
	v_cvt_pk_bf16_f32 v191, v34, v35
	ds_write_b64 v170, v[184:185] offset:8192
	ds_write_b64 v171, v[186:187] offset:8192
	ds_write_b64 v168, v[188:189] offset:8192
	ds_write_b64 v169, v[190:191] offset:8192
	v_cvt_pk_bf16_f32 v176, v28, v29
	v_cvt_pk_bf16_f32 v177, v30, v31
	v_cvt_pk_bf16_f32 v178, v20, v21
	v_cvt_pk_bf16_f32 v179, v22, v23
	v_cvt_pk_bf16_f32 v180, v24, v25
	v_cvt_pk_bf16_f32 v181, v26, v27
	v_cvt_pk_bf16_f32 v182, v16, v17
	v_cvt_pk_bf16_f32 v183, v18, v19
	ds_write_b64 v168, v[176:177] offset:16384
	ds_write_b64 v169, v[178:179] offset:16384
	ds_write_b64 v170, v[180:181] offset:16384
	ds_write_b64 v171, v[182:183] offset:16384
	v_cvt_pk_bf16_f32 v184, v12, v13
	v_cvt_pk_bf16_f32 v185, v14, v15
	v_cvt_pk_bf16_f32 v186, v8, v9
	v_cvt_pk_bf16_f32 v187, v10, v11
	v_cvt_pk_bf16_f32 v188, v4, v5
	v_cvt_pk_bf16_f32 v189, v6, v7
	v_cvt_pk_bf16_f32 v190, v0, v1
	v_cvt_pk_bf16_f32 v191, v2, v3
	ds_write_b64 v170, v[184:185] offset:24576
	ds_write_b64 v171, v[186:187] offset:24576
	ds_write_b64 v168, v[188:189] offset:24576
	ds_write_b64 v169, v[190:191] offset:24576
	s_waitcnt lgkmcnt(0)
	s_barrier
; __device__ __forceinline__ bf16_t f2bf(float f) { return (bf16_t)(pack2(f, 0.f) & 0xffffu); }
; __device__ __forceinline__ float siluf_(float x) { return x * __builtin_amdgcn_rcpf(1.f + __expf(-x)); }
; template <int EPI>
; __device__ __forceinline__ void gemm_tile8p(const bf16_t* __restrict__ Ag, const bf16_t* __restrict__ Bg, int K, int nt, int brow, int bcol,
;                                             char* smem, void* outp, int ldo, int nvalid, int rowoff, int rowlim) {
;     ...
; #pragma unroll
;   for (int ai = 0; ai < 2; ++ai)
; #pragma unroll
;     for (int m = 0; m < 4; ++m)
; #pragma unroll
;       for (int j = 0; j < 4; ++j) {
;         const int rl = ai * HALF + wr * 64 + m * 16 + fq * 4 + j;
;         const size_t orow = (size_t)(rowoff + rl) * ldo;
;         if (EPI == EPI_GLU) {
; #pragma unroll
;           for (int n = 0; n < 2; ++n) {
;             const int col = (bcol >> 8) * 128 + wc * 32 + n * 16 + fr;
;             const float g = acc[ai][0][m][n][j], u = acc[ai][1][m][n][j];
;             if (rl < rowlim) ((bf16_t*)outp)[orow + col] = f2bf(siluf_(g) * u);
;           }
;         } else {
; #pragma unroll
;           for (int bj = 0; bj < 2; ++bj)
; #pragma unroll
;             for (int n = 0; n < 2; ++n) {
;               const int col = bcol + bj * HALF + wc * 32 + n * 16 + fr;
;               const float v = acc[ai][bj][m][n][j];
;               if (EPI == EPI_BF16) { if (rl < rowlim && col < nvalid) ((bf16_t*)outp)[orow + col] = f2bf(v); }
;               else { if (rl < rowlim) ((float*)outp)[orow + col] = v; }
;             }
;         }
;         __builtin_amdgcn_sched_barrier(0);
;       }
	v_lshrrev_b32_e32 v160, 6, v136
	v_lshl_or_b32 v160, v160, 2, v133
	v_lshlrev_b32_e32 v160, 5, v160
	v_or_b32_e32 v160, v160, v161
	v_and_b32_e32 v162, 1, v135
	v_lshl_or_b32 v162, v162, 4, v134
	v_xor_b32_e32 v163, v162, v161
	v_lshlrev_b32_e32 v164, 9, v160
	v_lshl_add_u32 v165, v162, 3, s38
	s_movk_i32 s0, 0xd08
	v_cmp_gt_i32_e64 s[40:41], s0, v165
	v_add_u32_e32 v166, s48, v160
	v_mov_b32_e32 v167, 0
	v_mov_b32_e32 v168, v165
	v_mov_b32_e32 v169, 0
	v_lshl_add_u64 v[168:169], v[168:169], 1, s[68:69]
	v_mad_u64_u32 v[168:169], vcc, v166, s72, v[168:169]
	s_mov_b32 s12, 0x3420
	s_mov_b32 s13, 0
	v_xor_b32_e32 v170, 0, v163
	v_lshl_add_u32 v170, v170, 4, v164
	ds_read_b128 v[176:179], v170 offset:0
	v_xor_b32_e32 v170, 2, v163
	v_lshl_add_u32 v170, v170, 4, v164
	ds_read_b128 v[180:183], v170 offset:1024
	v_xor_b32_e32 v170, 4, v163
	v_lshl_add_u32 v170, v170, 4, v164
	ds_read_b128 v[184:187], v170 offset:2048
	v_xor_b32_e32 v170, 6, v163
	v_lshl_add_u32 v170, v170, 4, v164
	ds_read_b128 v[188:191], v170 offset:3072
	v_add_u32_e32 v171, 0, v160
	v_cmp_gt_i32_e64 s[2:3], s4, v171
	s_waitcnt lgkmcnt(3)
	s_and_b64 exec, s[2:3], s[40:41]
	global_store_dwordx4 v[168:169], v[176:179], off
	s_mov_b64 exec, -1
	v_lshl_add_u64 v[168:169], v[168:169], 0, s[12:13]
	v_add_u32_e32 v171, 2, v160
	v_cmp_gt_i32_e64 s[2:3], s4, v171
	s_waitcnt lgkmcnt(2)
	s_and_b64 exec, s[2:3], s[40:41]
	global_store_dwordx4 v[168:169], v[180:183], off
	s_mov_b64 exec, -1
	v_lshl_add_u64 v[168:169], v[168:169], 0, s[12:13]
	v_add_u32_e32 v171, 4, v160
	v_cmp_gt_i32_e64 s[2:3], s4, v171
	s_waitcnt lgkmcnt(1)
	s_and_b64 exec, s[2:3], s[40:41]
	global_store_dwordx4 v[168:169], v[184:187], off
	s_mov_b64 exec, -1
	v_lshl_add_u64 v[168:169], v[168:169], 0, s[12:13]
	v_add_u32_e32 v171, 6, v160
	v_cmp_gt_i32_e64 s[2:3], s4, v171
	s_waitcnt lgkmcnt(0)
	s_and_b64 exec, s[2:3], s[40:41]
	global_store_dwordx4 v[168:169], v[188:191], off
	s_mov_b64 exec, -1
	v_lshl_add_u64 v[168:169], v[168:169], 0, s[12:13]
	v_xor_b32_e32 v170, 8, v163
	v_lshl_add_u32 v170, v170, 4, v164
	ds_read_b128 v[176:179], v170 offset:4096
	v_xor_b32_e32 v170, 10, v163
	v_lshl_add_u32 v170, v170, 4, v164
	ds_read_b128 v[180:183], v170 offset:5120
	v_xor_b32_e32 v170, 12, v163
	v_lshl_add_u32 v170, v170, 4, v164
	ds_read_b128 v[184:187], v170 offset:6144
	v_xor_b32_e32 v170, 14, v163
	v_lshl_add_u32 v170, v170, 4, v164
	ds_read_b128 v[188:191], v170 offset:7168
	v_add_u32_e32 v171, 8, v160
	v_cmp_gt_i32_e64 s[2:3], s4, v171
	s_waitcnt lgkmcnt(3)
	s_and_b64 exec, s[2:3], s[40:41]
	global_store_dwordx4 v[168:169], v[176:179], off
	s_mov_b64 exec, -1
	v_lshl_add_u64 v[168:169], v[168:169], 0, s[12:13]
	v_add_u32_e32 v171, 10, v160
	v_cmp_gt_i32_e64 s[2:3], s4, v171
	s_waitcnt lgkmcnt(2)
	s_and_b64 exec, s[2:3], s[40:41]
	global_store_dwordx4 v[168:169], v[180:183], off
	s_mov_b64 exec, -1
	v_lshl_add_u64 v[168:169], v[168:169], 0, s[12:13]
	v_add_u32_e32 v171, 12, v160
	v_cmp_gt_i32_e64 s[2:3], s4, v171
	s_waitcnt lgkmcnt(1)
	s_and_b64 exec, s[2:3], s[40:41]
	global_store_dwordx4 v[168:169], v[184:187], off
	s_mov_b64 exec, -1
	v_lshl_add_u64 v[168:169], v[168:169], 0, s[12:13]
	v_add_u32_e32 v171, 14, v160
	v_cmp_gt_i32_e64 s[2:3], s4, v171
	s_waitcnt lgkmcnt(0)
	s_and_b64 exec, s[2:3], s[40:41]
	global_store_dwordx4 v[168:169], v[188:191], off
	s_mov_b64 exec, -1
	v_lshl_add_u64 v[168:169], v[168:169], 0, s[12:13]
	v_xor_b32_e32 v170, 16, v163
	v_lshl_add_u32 v170, v170, 4, v164
	ds_read_b128 v[176:179], v170 offset:8192
	v_xor_b32_e32 v170, 18, v163
	v_lshl_add_u32 v170, v170, 4, v164
	ds_read_b128 v[180:183], v170 offset:9216
	v_xor_b32_e32 v170, 20, v163
	v_lshl_add_u32 v170, v170, 4, v164
	ds_read_b128 v[184:187], v170 offset:10240
	v_xor_b32_e32 v170, 22, v163
	v_lshl_add_u32 v170, v170, 4, v164
	ds_read_b128 v[188:191], v170 offset:11264
	v_add_u32_e32 v171, 16, v160
	v_cmp_gt_i32_e64 s[2:3], s4, v171
	s_waitcnt lgkmcnt(3)
	s_and_b64 exec, s[2:3], s[40:41]
	global_store_dwordx4 v[168:169], v[176:179], off
	s_mov_b64 exec, -1
	v_lshl_add_u64 v[168:169], v[168:169], 0, s[12:13]
	v_add_u32_e32 v171, 18, v160
	v_cmp_gt_i32_e64 s[2:3], s4, v171
	s_waitcnt lgkmcnt(2)
	s_and_b64 exec, s[2:3], s[40:41]
	global_store_dwordx4 v[168:169], v[180:183], off
	s_mov_b64 exec, -1
	v_lshl_add_u64 v[168:169], v[168:169], 0, s[12:13]
	v_add_u32_e32 v171, 20, v160
	v_cmp_gt_i32_e64 s[2:3], s4, v171
	s_waitcnt lgkmcnt(1)
	s_and_b64 exec, s[2:3], s[40:41]
	global_store_dwordx4 v[168:169], v[184:187], off
	s_mov_b64 exec, -1
	v_lshl_add_u64 v[168:169], v[168:169], 0, s[12:13]
	v_add_u32_e32 v171, 22, v160
	v_cmp_gt_i32_e64 s[2:3], s4, v171
	s_waitcnt lgkmcnt(0)
	s_and_b64 exec, s[2:3], s[40:41]
	global_store_dwordx4 v[168:169], v[188:191], off
	s_mov_b64 exec, -1
	v_lshl_add_u64 v[168:169], v[168:169], 0, s[12:13]
	v_xor_b32_e32 v170, 24, v163
	v_lshl_add_u32 v170, v170, 4, v164
	ds_read_b128 v[176:179], v170 offset:12288
	v_xor_b32_e32 v170, 26, v163
	v_lshl_add_u32 v170, v170, 4, v164
	ds_read_b128 v[180:183], v170 offset:13312
	v_xor_b32_e32 v170, 28, v163
	v_lshl_add_u32 v170, v170, 4, v164
	ds_read_b128 v[184:187], v170 offset:14336
	v_xor_b32_e32 v170, 30, v163
	v_lshl_add_u32 v170, v170, 4, v164
	ds_read_b128 v[188:191], v170 offset:15360
	v_add_u32_e32 v171, 24, v160
	v_cmp_gt_i32_e64 s[2:3], s4, v171
	s_waitcnt lgkmcnt(3)
	s_and_b64 exec, s[2:3], s[40:41]
	global_store_dwordx4 v[168:169], v[176:179], off
	s_mov_b64 exec, -1
	v_lshl_add_u64 v[168:169], v[168:169], 0, s[12:13]
	v_add_u32_e32 v171, 26, v160
	v_cmp_gt_i32_e64 s[2:3], s4, v171
	s_waitcnt lgkmcnt(2)
	s_and_b64 exec, s[2:3], s[40:41]
	global_store_dwordx4 v[168:169], v[180:183], off
	s_mov_b64 exec, -1
	v_lshl_add_u64 v[168:169], v[168:169], 0, s[12:13]
	v_add_u32_e32 v171, 28, v160
	v_cmp_gt_i32_e64 s[2:3], s4, v171
	s_waitcnt lgkmcnt(1)
	s_and_b64 exec, s[2:3], s[40:41]
	global_store_dwordx4 v[168:169], v[184:187], off
	s_mov_b64 exec, -1
	v_lshl_add_u64 v[168:169], v[168:169], 0, s[12:13]
	v_add_u32_e32 v171, 30, v160
	v_cmp_gt_i32_e64 s[2:3], s4, v171
	s_waitcnt lgkmcnt(0)
	s_and_b64 exec, s[2:3], s[40:41]
	global_store_dwordx4 v[168:169], v[188:191], off
	s_mov_b64 exec, -1
	v_lshl_add_u64 v[168:169], v[168:169], 0, s[12:13]
	s_branch .LBB0_1060
